# GEMM K-loops: drop mid s_setprio 0/1 pairs and the redundant post-barrier lgkmcnt(0)
# speedup vs baseline: 1.0050x; 1.0050x over previous
.LBB0_176:
	ds_read_b128 v[58:61], v219
	ds_read_b128 v[62:65], v219 offset:1024
	ds_read_b128 v[78:81], v219 offset:2048
	ds_read_b128 v[82:85], v219 offset:3072
	ds_read_b128 v[102:105], v220
	ds_read_b128 v[106:109], v220 offset:1024
	ds_read_b128 v[122:125], v220 offset:2048
	ds_read_b128 v[126:129], v220 offset:3072
	s_add_u32 s42, s40, 0xfff80080
	s_addc_u32 s43, s41, -1
	s_cmp_eq_u32 s52, 28
	s_cselect_b32 s45, s2, s43
	s_cselect_b32 s44, s29, s42
	s_cselect_b32 s43, s27, s47
	s_cselect_b32 s42, s39, s46
	v_lshl_add_u64 v[212:213], s[40:41], 0, v[206:207]
	s_add_i32 m0, s49, 0xc000
	ds_read_b128 v[146:149], v221
	ds_read_b128 v[150:153], v221 offset:1024
	ds_read_b128 v[170:173], v221 offset:2048
	ds_read_b128 v[174:177], v221 offset:3072
	ds_read_b128 v[178:181], v221 offset:4096
	ds_read_b128 v[182:185], v221 offset:5120
	ds_read_b128 v[186:189], v221 offset:6144
	ds_read_b128 v[190:193], v221 offset:7168
	global_load_lds_dwordx4 v[212:213], off
	v_lshl_add_u64 v[212:213], s[40:41], 0, v[208:209]
	s_add_i32 m0, s49, 0xe000
	s_nop 0
	global_load_lds_dwordx4 v[212:213], off
	s_waitcnt vmcnt(8)
	s_waitcnt lgkmcnt(0)
	s_barrier
	s_setprio 1
	v_mfma_f32_16x16x32_bf16 v[166:169], v[58:61], v[146:149], v[166:169]
	v_mfma_f32_16x16x32_bf16 v[162:165], v[78:81], v[146:149], v[162:165]
	v_mfma_f32_16x16x32_bf16 v[142:145], v[58:61], v[170:173], v[142:145]
	v_mfma_f32_16x16x32_bf16 v[138:141], v[78:81], v[170:173], v[138:141]
	v_mfma_f32_16x16x32_bf16 v[118:121], v[58:61], v[178:181], v[118:121]
	v_mfma_f32_16x16x32_bf16 v[114:117], v[78:81], v[178:181], v[114:117]
	v_mfma_f32_16x16x32_bf16 v[94:97], v[58:61], v[186:189], v[94:97]
	v_mfma_f32_16x16x32_bf16 v[90:93], v[78:81], v[186:189], v[90:93]
	v_mfma_f32_16x16x32_bf16 v[166:169], v[62:65], v[150:153], v[166:169]
	v_mfma_f32_16x16x32_bf16 v[162:165], v[82:85], v[150:153], v[162:165]
	v_mfma_f32_16x16x32_bf16 v[142:145], v[62:65], v[174:177], v[142:145]
	v_mfma_f32_16x16x32_bf16 v[138:141], v[82:85], v[174:177], v[138:141]
	v_mfma_f32_16x16x32_bf16 v[118:121], v[62:65], v[182:185], v[118:121]
	v_mfma_f32_16x16x32_bf16 v[114:117], v[82:85], v[182:185], v[114:117]
	v_mfma_f32_16x16x32_bf16 v[94:97], v[62:65], v[190:193], v[94:97]
	v_mfma_f32_16x16x32_bf16 v[90:93], v[82:85], v[190:193], v[90:93]
	v_mfma_f32_16x16x32_bf16 v[158:161], v[102:105], v[146:149], v[158:161]
	v_mfma_f32_16x16x32_bf16 v[134:137], v[102:105], v[170:173], v[134:137]
	v_mfma_f32_16x16x32_bf16 v[130:133], v[122:125], v[170:173], v[130:133]
	v_mfma_f32_16x16x32_bf16 v[110:113], v[102:105], v[178:181], v[110:113]
	v_mfma_f32_16x16x32_bf16 v[98:101], v[122:125], v[178:181], v[98:101]
	v_mfma_f32_16x16x32_bf16 v[86:89], v[102:105], v[186:189], v[86:89]
	v_mfma_f32_16x16x32_bf16 v[74:77], v[122:125], v[186:189], v[74:77]
	v_mfma_f32_16x16x32_bf16 v[158:161], v[106:109], v[150:153], v[158:161]
	v_mfma_f32_16x16x32_bf16 v[146:149], v[122:125], v[146:149], v[154:157]
	v_mfma_f32_16x16x32_bf16 v[134:137], v[106:109], v[174:177], v[134:137]
	v_mfma_f32_16x16x32_bf16 v[130:133], v[126:129], v[174:177], v[130:133]
	v_mfma_f32_16x16x32_bf16 v[110:113], v[106:109], v[182:185], v[110:113]
	v_mfma_f32_16x16x32_bf16 v[98:101], v[126:129], v[182:185], v[98:101]
	v_mfma_f32_16x16x32_bf16 v[86:89], v[106:109], v[190:193], v[86:89]
	v_mfma_f32_16x16x32_bf16 v[74:77], v[126:129], v[190:193], v[74:77]
	v_mfma_f32_16x16x32_bf16 v[146:149], v[126:129], v[150:153], v[146:149]
	s_setprio 0
	s_barrier
	s_add_i32 s53, s86, s48
	v_lshl_add_u64 v[212:213], s[42:43], 0, v[198:199]
	s_mov_b32 m0, s53
	ds_read_b128 v[150:153], v221 offset:16384
	ds_read_b128 v[154:157], v221 offset:17408
	ds_read_b128 v[170:173], v221 offset:18432
	ds_read_b128 v[174:177], v221 offset:19456
	ds_read_b128 v[178:181], v221 offset:20480
	ds_read_b128 v[182:185], v221 offset:21504
	ds_read_b128 v[186:189], v221 offset:22528
	ds_read_b128 v[190:193], v221 offset:23552
	global_load_lds_dwordx4 v[212:213], off
	s_add_i32 m0, s53, 0x2000
	s_add_u32 s54, s42, 0x80000
	v_lshl_add_u64 v[214:215], s[42:43], 0, v[202:203]
	s_addc_u32 s55, s43, 0
	s_add_i32 s53, s87, s48
	global_load_lds_dwordx4 v[214:215], off
	v_lshl_add_u64 v[216:217], s[54:55], 0, v[198:199]
	s_mov_b32 m0, s53
	v_lshl_add_u64 v[222:223], s[44:45], 0, v[200:201]
	global_load_lds_dwordx4 v[216:217], off
	v_lshl_add_u64 v[216:217], s[54:55], 0, v[202:203]
	s_add_i32 m0, s53, 0x2000
	s_nop 0
	global_load_lds_dwordx4 v[216:217], off
	v_lshl_add_u64 v[216:217], s[44:45], 0, v[196:197]
	s_mov_b32 m0, s49
	s_nop 0
	global_load_lds_dwordx4 v[216:217], off
	s_mov_b32 m0, s50
	s_nop 0
	global_load_lds_dwordx4 v[222:223], off
	s_waitcnt vmcnt(8)
	s_waitcnt lgkmcnt(0)
	s_barrier
	s_setprio 1
	v_mfma_f32_16x16x32_bf16 v[70:73], v[58:61], v[150:153], v[70:73]
	v_mfma_f32_16x16x32_bf16 v[66:69], v[78:81], v[150:153], v[66:69]
	v_mfma_f32_16x16x32_bf16 v[46:49], v[58:61], v[170:173], v[46:49]
	v_mfma_f32_16x16x32_bf16 v[42:45], v[78:81], v[170:173], v[42:45]
	v_mfma_f32_16x16x32_bf16 v[30:33], v[58:61], v[178:181], v[30:33]
	v_mfma_f32_16x16x32_bf16 v[26:29], v[78:81], v[178:181], v[26:29]
	v_mfma_f32_16x16x32_bf16 v[14:17], v[58:61], v[186:189], v[14:17]
	v_mfma_f32_16x16x32_bf16 v[10:13], v[78:81], v[186:189], v[10:13]
	v_mfma_f32_16x16x32_bf16 v[70:73], v[62:65], v[154:157], v[70:73]
	v_mfma_f32_16x16x32_bf16 v[66:69], v[82:85], v[154:157], v[66:69]
	v_mfma_f32_16x16x32_bf16 v[46:49], v[62:65], v[174:177], v[46:49]
	v_mfma_f32_16x16x32_bf16 v[42:45], v[82:85], v[174:177], v[42:45]
	v_mfma_f32_16x16x32_bf16 v[30:33], v[62:65], v[182:185], v[30:33]
	v_mfma_f32_16x16x32_bf16 v[26:29], v[82:85], v[182:185], v[26:29]
	v_mfma_f32_16x16x32_bf16 v[14:17], v[62:65], v[190:193], v[14:17]
	v_mfma_f32_16x16x32_bf16 v[10:13], v[82:85], v[190:193], v[10:13]
	v_mfma_f32_16x16x32_bf16 v[54:57], v[102:105], v[150:153], v[54:57]
	v_mfma_f32_16x16x32_bf16 v[50:53], v[122:125], v[150:153], v[50:53]
	v_mfma_f32_16x16x32_bf16 v[38:41], v[102:105], v[170:173], v[38:41]
	v_mfma_f32_16x16x32_bf16 v[34:37], v[122:125], v[170:173], v[34:37]
	v_mfma_f32_16x16x32_bf16 v[22:25], v[102:105], v[178:181], v[22:25]
	v_mfma_f32_16x16x32_bf16 v[18:21], v[122:125], v[178:181], v[18:21]
	v_mfma_f32_16x16x32_bf16 v[6:9], v[102:105], v[186:189], v[6:9]
	v_mfma_f32_16x16x32_bf16 v[2:5], v[122:125], v[186:189], v[2:5]
	v_mfma_f32_16x16x32_bf16 v[54:57], v[106:109], v[154:157], v[54:57]
	v_mfma_f32_16x16x32_bf16 v[50:53], v[126:129], v[154:157], v[50:53]
	v_mfma_f32_16x16x32_bf16 v[38:41], v[106:109], v[174:177], v[38:41]
	v_mfma_f32_16x16x32_bf16 v[34:37], v[126:129], v[174:177], v[34:37]
	v_mfma_f32_16x16x32_bf16 v[22:25], v[106:109], v[182:185], v[22:25]
	v_mfma_f32_16x16x32_bf16 v[18:21], v[126:129], v[182:185], v[18:21]
	v_mfma_f32_16x16x32_bf16 v[6:9], v[106:109], v[190:193], v[6:9]
	v_mfma_f32_16x16x32_bf16 v[2:5], v[126:129], v[190:193], v[2:5]
	s_setprio 0
	s_barrier
	s_add_i32 s53, 0, 0x18000
	s_add_i32 s54, 0, 0x1c000
	v_add_u32_e32 v82, s53, v218
	v_add_u32_e32 v126, s54, v218
	ds_read_b128 v[58:61], v82
	ds_read_b128 v[62:65], v82 offset:1024
	ds_read_b128 v[78:81], v82 offset:2048
	ds_read_b128 v[82:85], v82 offset:3072
	ds_read_b128 v[102:105], v126
	ds_read_b128 v[106:109], v126 offset:1024
	ds_read_b128 v[122:125], v126 offset:2048
	ds_read_b128 v[126:129], v126 offset:3072
	s_add_u32 s44, s44, 0x80000
	s_addc_u32 s45, s45, 0
	s_mov_b32 m0, s51
	v_lshl_add_u64 v[224:225], s[44:45], 0, v[196:197]
	ds_read_b128 v[150:153], v221 offset:32768
	ds_read_b128 v[154:157], v221 offset:33792
	ds_read_b128 v[170:173], v221 offset:34816
	ds_read_b128 v[174:177], v221 offset:35840
	ds_read_b128 v[178:181], v221 offset:36864
	ds_read_b128 v[182:185], v221 offset:37888
	ds_read_b128 v[186:189], v221 offset:38912
	ds_read_b128 v[190:193], v221 offset:39936
	global_load_lds_dwordx4 v[224:225], off
	v_lshl_add_u64 v[224:225], s[44:45], 0, v[200:201]
	s_mov_b32 m0, s72
	s_nop 0
	global_load_lds_dwordx4 v[224:225], off
	s_waitcnt vmcnt(8)
	s_waitcnt lgkmcnt(0)
	s_barrier
	s_setprio 1
	v_mfma_f32_16x16x32_bf16 v[166:169], v[58:61], v[150:153], v[166:169]
	v_mfma_f32_16x16x32_bf16 v[162:165], v[78:81], v[150:153], v[162:165]
	v_mfma_f32_16x16x32_bf16 v[142:145], v[58:61], v[170:173], v[142:145]
	v_mfma_f32_16x16x32_bf16 v[138:141], v[78:81], v[170:173], v[138:141]
	v_mfma_f32_16x16x32_bf16 v[118:121], v[58:61], v[178:181], v[118:121]
	v_mfma_f32_16x16x32_bf16 v[114:117], v[78:81], v[178:181], v[114:117]
	v_mfma_f32_16x16x32_bf16 v[94:97], v[58:61], v[186:189], v[94:97]
	v_mfma_f32_16x16x32_bf16 v[90:93], v[78:81], v[186:189], v[90:93]
	v_mfma_f32_16x16x32_bf16 v[166:169], v[62:65], v[154:157], v[166:169]
	v_mfma_f32_16x16x32_bf16 v[162:165], v[82:85], v[154:157], v[162:165]
	v_mfma_f32_16x16x32_bf16 v[142:145], v[62:65], v[174:177], v[142:145]
	v_mfma_f32_16x16x32_bf16 v[138:141], v[82:85], v[174:177], v[138:141]
	v_mfma_f32_16x16x32_bf16 v[118:121], v[62:65], v[182:185], v[118:121]
	v_mfma_f32_16x16x32_bf16 v[114:117], v[82:85], v[182:185], v[114:117]
	v_mfma_f32_16x16x32_bf16 v[94:97], v[62:65], v[190:193], v[94:97]
	v_mfma_f32_16x16x32_bf16 v[90:93], v[82:85], v[190:193], v[90:93]
	v_mfma_f32_16x16x32_bf16 v[158:161], v[102:105], v[150:153], v[158:161]
	v_mfma_f32_16x16x32_bf16 v[146:149], v[122:125], v[150:153], v[146:149]
	v_mfma_f32_16x16x32_bf16 v[134:137], v[102:105], v[170:173], v[134:137]
	v_mfma_f32_16x16x32_bf16 v[130:133], v[122:125], v[170:173], v[130:133]
	v_mfma_f32_16x16x32_bf16 v[110:113], v[102:105], v[178:181], v[110:113]
	v_mfma_f32_16x16x32_bf16 v[98:101], v[122:125], v[178:181], v[98:101]
	v_mfma_f32_16x16x32_bf16 v[86:89], v[102:105], v[186:189], v[86:89]
	v_mfma_f32_16x16x32_bf16 v[74:77], v[122:125], v[186:189], v[74:77]
	v_mfma_f32_16x16x32_bf16 v[158:161], v[106:109], v[154:157], v[158:161]
	v_mfma_f32_16x16x32_bf16 v[154:157], v[126:129], v[154:157], v[146:149]
	v_mfma_f32_16x16x32_bf16 v[134:137], v[106:109], v[174:177], v[134:137]
	v_mfma_f32_16x16x32_bf16 v[130:133], v[126:129], v[174:177], v[130:133]
	v_mfma_f32_16x16x32_bf16 v[110:113], v[106:109], v[182:185], v[110:113]
	v_mfma_f32_16x16x32_bf16 v[98:101], v[126:129], v[182:185], v[98:101]
	v_mfma_f32_16x16x32_bf16 v[86:89], v[106:109], v[190:193], v[86:89]
	v_mfma_f32_16x16x32_bf16 v[74:77], v[126:129], v[190:193], v[74:77]
	s_setprio 0
	s_barrier
	s_add_i32 s44, s53, s48
	v_lshl_add_u64 v[212:213], v[212:213], 0, s[12:13]
	s_mov_b32 m0, s44
	ds_read_b128 v[146:149], v221 offset:49152
	ds_read_b128 v[150:153], v221 offset:50176
	ds_read_b128 v[170:173], v221 offset:51200
	ds_read_b128 v[174:177], v221 offset:52224
	ds_read_b128 v[178:181], v221 offset:53248
	ds_read_b128 v[182:185], v221 offset:54272
	ds_read_b128 v[186:189], v221 offset:55296
	ds_read_b128 v[190:193], v221 offset:56320
	global_load_lds_dwordx4 v[212:213], off
	s_add_i32 m0, s44, 0x2000
	s_add_u32 s42, s42, 0x80080
	v_lshl_add_u64 v[212:213], v[214:215], 0, s[12:13]
	s_addc_u32 s43, s43, 0
	s_add_i32 s44, s54, s48
	global_load_lds_dwordx4 v[212:213], off
	v_lshl_add_u64 v[212:213], s[42:43], 0, v[198:199]
	s_mov_b32 m0, s44
	s_nop 0
	global_load_lds_dwordx4 v[212:213], off
	v_lshl_add_u64 v[212:213], s[42:43], 0, v[202:203]
	s_add_i32 m0, s44, 0x2000
	s_nop 0
	global_load_lds_dwordx4 v[212:213], off
	v_lshl_add_u64 v[212:213], v[216:217], 0, s[12:13]
	s_mov_b32 m0, s79
	s_nop 0
	global_load_lds_dwordx4 v[212:213], off
	v_lshl_add_u64 v[212:213], v[222:223], 0, s[12:13]
	s_mov_b32 m0, s80
	s_nop 0
	global_load_lds_dwordx4 v[212:213], off
	s_waitcnt vmcnt(8)
	s_waitcnt lgkmcnt(0)
	s_barrier
	s_setprio 1
	v_mfma_f32_16x16x32_bf16 v[70:73], v[58:61], v[146:149], v[70:73]
	v_mfma_f32_16x16x32_bf16 v[66:69], v[78:81], v[146:149], v[66:69]
	v_mfma_f32_16x16x32_bf16 v[46:49], v[58:61], v[170:173], v[46:49]
	v_mfma_f32_16x16x32_bf16 v[42:45], v[78:81], v[170:173], v[42:45]
	v_mfma_f32_16x16x32_bf16 v[30:33], v[58:61], v[178:181], v[30:33]
	v_mfma_f32_16x16x32_bf16 v[26:29], v[78:81], v[178:181], v[26:29]
	v_mfma_f32_16x16x32_bf16 v[14:17], v[58:61], v[186:189], v[14:17]
	v_mfma_f32_16x16x32_bf16 v[10:13], v[78:81], v[186:189], v[10:13]
	v_mfma_f32_16x16x32_bf16 v[70:73], v[62:65], v[150:153], v[70:73]
	v_mfma_f32_16x16x32_bf16 v[66:69], v[82:85], v[150:153], v[66:69]
	v_mfma_f32_16x16x32_bf16 v[46:49], v[62:65], v[174:177], v[46:49]
	v_mfma_f32_16x16x32_bf16 v[42:45], v[82:85], v[174:177], v[42:45]
	v_mfma_f32_16x16x32_bf16 v[30:33], v[62:65], v[182:185], v[30:33]
	v_mfma_f32_16x16x32_bf16 v[26:29], v[82:85], v[182:185], v[26:29]
	v_mfma_f32_16x16x32_bf16 v[14:17], v[62:65], v[190:193], v[14:17]
	v_mfma_f32_16x16x32_bf16 v[10:13], v[82:85], v[190:193], v[10:13]
	v_mfma_f32_16x16x32_bf16 v[54:57], v[102:105], v[146:149], v[54:57]
	v_mfma_f32_16x16x32_bf16 v[50:53], v[122:125], v[146:149], v[50:53]
	v_mfma_f32_16x16x32_bf16 v[38:41], v[102:105], v[170:173], v[38:41]
	v_mfma_f32_16x16x32_bf16 v[34:37], v[122:125], v[170:173], v[34:37]
	v_mfma_f32_16x16x32_bf16 v[22:25], v[102:105], v[178:181], v[22:25]
	v_mfma_f32_16x16x32_bf16 v[18:21], v[122:125], v[178:181], v[18:21]
	v_mfma_f32_16x16x32_bf16 v[6:9], v[102:105], v[186:189], v[6:9]
	v_mfma_f32_16x16x32_bf16 v[2:5], v[122:125], v[186:189], v[2:5]
	v_mfma_f32_16x16x32_bf16 v[54:57], v[106:109], v[150:153], v[54:57]
	v_mfma_f32_16x16x32_bf16 v[50:53], v[126:129], v[150:153], v[50:53]
	v_mfma_f32_16x16x32_bf16 v[38:41], v[106:109], v[174:177], v[38:41]
	v_mfma_f32_16x16x32_bf16 v[34:37], v[126:129], v[174:177], v[34:37]
	v_mfma_f32_16x16x32_bf16 v[22:25], v[106:109], v[182:185], v[22:25]
	v_mfma_f32_16x16x32_bf16 v[18:21], v[126:129], v[182:185], v[18:21]
	v_mfma_f32_16x16x32_bf16 v[6:9], v[106:109], v[190:193], v[6:9]
	v_mfma_f32_16x16x32_bf16 v[2:5], v[126:129], v[190:193], v[2:5]
	s_setprio 0
	s_barrier
	s_add_i32 s52, s52, 2
	s_add_u32 s46, s46, 0x100
	s_addc_u32 s47, s47, 0
	s_add_u32 s40, s40, 0x100
	s_addc_u32 s41, s41, 0
	s_cmp_gt_u32 s52, 29
	s_cbranch_scc0 .LBB0_176
	s_and_b64 vcc, exec, s[24:25]
	s_cbranch_vccz .LBB0_179
	s_barrier

.LBB0_651:
	ds_read_b128 v[140:143], v197
	ds_read_b128 v[144:147], v197 offset:1024
	ds_read_b128 v[148:151], v197 offset:2048
	ds_read_b128 v[152:155], v197 offset:3072
	ds_read_b128 v[156:159], v198
	ds_read_b128 v[160:163], v198 offset:1024
	ds_read_b128 v[164:167], v198 offset:2048
	ds_read_b128 v[168:171], v198 offset:3072
	s_add_u32 s28, s26, 0xfff80080
	s_addc_u32 s29, s27, -1
	s_cmp_eq_u32 s46, 28
	s_cselect_b32 s31, s15, s29
	s_cselect_b32 s30, s23, s28
	s_cselect_b32 s29, s13, s45
	s_cselect_b32 s28, s43, s44
	v_lshl_add_u64 v[192:193], s[26:27], 0, v[134:135]
	s_add_i32 m0, s25, 0xc000
	ds_read_b128 v[172:175], v199
	ds_read_b128 v[176:179], v199 offset:1024
	ds_read_b128 v[180:183], v199 offset:2048
	ds_read_b128 v[184:187], v199 offset:3072
	ds_read_b128 v[188:191], v199 offset:4096
	ds_read_b128 v[202:205], v199 offset:5120
	ds_read_b128 v[206:209], v199 offset:6144
	ds_read_b128 v[210:213], v199 offset:7168
	global_load_lds_dwordx4 v[192:193], off
	v_lshl_add_u64 v[192:193], s[26:27], 0, v[136:137]
	s_add_i32 m0, s25, 0xe000
	s_nop 0
	global_load_lds_dwordx4 v[192:193], off
	s_waitcnt vmcnt(8)
	s_waitcnt lgkmcnt(0)
	s_barrier
	s_setprio 1
	v_mfma_f32_16x16x32_bf16 v[126:129], v[140:143], v[172:175], v[126:129]
	v_mfma_f32_16x16x32_bf16 v[122:125], v[148:151], v[172:175], v[122:125]
	v_mfma_f32_16x16x32_bf16 v[110:113], v[140:143], v[180:183], v[110:113]
	v_mfma_f32_16x16x32_bf16 v[106:109], v[148:151], v[180:183], v[106:109]
	v_mfma_f32_16x16x32_bf16 v[94:97], v[140:143], v[188:191], v[94:97]
	v_mfma_f32_16x16x32_bf16 v[90:93], v[148:151], v[188:191], v[90:93]
	v_mfma_f32_16x16x32_bf16 v[78:81], v[140:143], v[206:209], v[78:81]
	v_mfma_f32_16x16x32_bf16 v[74:77], v[148:151], v[206:209], v[74:77]
	v_mfma_f32_16x16x32_bf16 v[126:129], v[144:147], v[176:179], v[126:129]
	v_mfma_f32_16x16x32_bf16 v[122:125], v[152:155], v[176:179], v[122:125]
	v_mfma_f32_16x16x32_bf16 v[110:113], v[144:147], v[184:187], v[110:113]
	v_mfma_f32_16x16x32_bf16 v[106:109], v[152:155], v[184:187], v[106:109]
	v_mfma_f32_16x16x32_bf16 v[94:97], v[144:147], v[202:205], v[94:97]
	v_mfma_f32_16x16x32_bf16 v[90:93], v[152:155], v[202:205], v[90:93]
	v_mfma_f32_16x16x32_bf16 v[78:81], v[144:147], v[210:213], v[78:81]
	v_mfma_f32_16x16x32_bf16 v[74:77], v[152:155], v[210:213], v[74:77]
	v_mfma_f32_16x16x32_bf16 v[118:121], v[156:159], v[172:175], v[118:121]
	v_mfma_f32_16x16x32_bf16 v[114:117], v[164:167], v[172:175], v[114:117]
	v_mfma_f32_16x16x32_bf16 v[102:105], v[156:159], v[180:183], v[102:105]
	v_mfma_f32_16x16x32_bf16 v[98:101], v[164:167], v[180:183], v[98:101]
	v_mfma_f32_16x16x32_bf16 v[86:89], v[156:159], v[188:191], v[86:89]
	v_mfma_f32_16x16x32_bf16 v[82:85], v[164:167], v[188:191], v[82:85]
	v_mfma_f32_16x16x32_bf16 v[70:73], v[156:159], v[206:209], v[70:73]
	v_mfma_f32_16x16x32_bf16 v[66:69], v[164:167], v[206:209], v[66:69]
	v_mfma_f32_16x16x32_bf16 v[118:121], v[160:163], v[176:179], v[118:121]
	v_mfma_f32_16x16x32_bf16 v[114:117], v[168:171], v[176:179], v[114:117]
	v_mfma_f32_16x16x32_bf16 v[102:105], v[160:163], v[184:187], v[102:105]
	v_mfma_f32_16x16x32_bf16 v[98:101], v[168:171], v[184:187], v[98:101]
	v_mfma_f32_16x16x32_bf16 v[86:89], v[160:163], v[202:205], v[86:89]
	v_mfma_f32_16x16x32_bf16 v[82:85], v[168:171], v[202:205], v[82:85]
	v_mfma_f32_16x16x32_bf16 v[70:73], v[160:163], v[210:213], v[70:73]
	v_mfma_f32_16x16x32_bf16 v[66:69], v[168:171], v[210:213], v[66:69]
	s_setprio 0
	s_barrier
	s_add_i32 s47, s2, s3
	v_lshl_add_u64 v[192:193], s[28:29], 0, v[130:131]
	s_mov_b32 m0, s47
	ds_read_b128 v[172:175], v199 offset:16384
	ds_read_b128 v[176:179], v199 offset:17408
	ds_read_b128 v[180:183], v199 offset:18432
	ds_read_b128 v[184:187], v199 offset:19456
	ds_read_b128 v[188:191], v199 offset:20480
	ds_read_b128 v[202:205], v199 offset:21504
	ds_read_b128 v[206:209], v199 offset:22528
	ds_read_b128 v[210:213], v199 offset:23552
	global_load_lds_dwordx4 v[192:193], off
	s_add_i32 m0, s47, 0x2000
	s_add_u32 s48, s28, 0x80000
	v_lshl_add_u64 v[214:215], s[28:29], 0, v[132:133]
	s_addc_u32 s49, s29, 0
	s_add_i32 s47, s42, s3
	global_load_lds_dwordx4 v[214:215], off
	v_lshl_add_u64 v[216:217], s[48:49], 0, v[130:131]
	s_mov_b32 m0, s47
	v_lshl_add_u64 v[218:219], s[30:31], 0, v[132:133]
	global_load_lds_dwordx4 v[216:217], off
	v_lshl_add_u64 v[216:217], s[48:49], 0, v[132:133]
	s_add_i32 m0, s47, 0x2000
	s_nop 0
	global_load_lds_dwordx4 v[216:217], off
	v_lshl_add_u64 v[216:217], s[30:31], 0, v[130:131]
	s_mov_b32 m0, s25
	s_nop 0
	global_load_lds_dwordx4 v[216:217], off
	s_mov_b32 m0, s34
	s_nop 0
	global_load_lds_dwordx4 v[218:219], off
	s_waitcnt vmcnt(8)
	s_waitcnt lgkmcnt(0)
	s_barrier
	s_setprio 1
	v_mfma_f32_16x16x32_bf16 v[62:65], v[140:143], v[172:175], v[62:65]
	v_mfma_f32_16x16x32_bf16 v[58:61], v[148:151], v[172:175], v[58:61]
	v_mfma_f32_16x16x32_bf16 v[46:49], v[140:143], v[180:183], v[46:49]
	v_mfma_f32_16x16x32_bf16 v[42:45], v[148:151], v[180:183], v[42:45]
	v_mfma_f32_16x16x32_bf16 v[30:33], v[140:143], v[188:191], v[30:33]
	v_mfma_f32_16x16x32_bf16 v[26:29], v[148:151], v[188:191], v[26:29]
	v_mfma_f32_16x16x32_bf16 v[14:17], v[140:143], v[206:209], v[14:17]
	v_mfma_f32_16x16x32_bf16 v[10:13], v[148:151], v[206:209], v[10:13]
	v_mfma_f32_16x16x32_bf16 v[62:65], v[144:147], v[176:179], v[62:65]
	v_mfma_f32_16x16x32_bf16 v[58:61], v[152:155], v[176:179], v[58:61]
	v_mfma_f32_16x16x32_bf16 v[46:49], v[144:147], v[184:187], v[46:49]
	v_mfma_f32_16x16x32_bf16 v[42:45], v[152:155], v[184:187], v[42:45]
	v_mfma_f32_16x16x32_bf16 v[30:33], v[144:147], v[202:205], v[30:33]
	v_mfma_f32_16x16x32_bf16 v[26:29], v[152:155], v[202:205], v[26:29]
	v_mfma_f32_16x16x32_bf16 v[14:17], v[144:147], v[210:213], v[14:17]
	v_mfma_f32_16x16x32_bf16 v[10:13], v[152:155], v[210:213], v[10:13]
	v_mfma_f32_16x16x32_bf16 v[54:57], v[156:159], v[172:175], v[54:57]
	v_mfma_f32_16x16x32_bf16 v[50:53], v[164:167], v[172:175], v[50:53]
	v_mfma_f32_16x16x32_bf16 v[38:41], v[156:159], v[180:183], v[38:41]
	v_mfma_f32_16x16x32_bf16 v[34:37], v[164:167], v[180:183], v[34:37]
	v_mfma_f32_16x16x32_bf16 v[22:25], v[156:159], v[188:191], v[22:25]
	v_mfma_f32_16x16x32_bf16 v[18:21], v[164:167], v[188:191], v[18:21]
	v_mfma_f32_16x16x32_bf16 v[6:9], v[156:159], v[206:209], v[6:9]
	v_mfma_f32_16x16x32_bf16 v[2:5], v[164:167], v[206:209], v[2:5]
	v_mfma_f32_16x16x32_bf16 v[54:57], v[160:163], v[176:179], v[54:57]
	v_mfma_f32_16x16x32_bf16 v[50:53], v[168:171], v[176:179], v[50:53]
	v_mfma_f32_16x16x32_bf16 v[38:41], v[160:163], v[184:187], v[38:41]
	v_mfma_f32_16x16x32_bf16 v[34:37], v[168:171], v[184:187], v[34:37]
	v_mfma_f32_16x16x32_bf16 v[22:25], v[160:163], v[202:205], v[22:25]
	v_mfma_f32_16x16x32_bf16 v[18:21], v[168:171], v[202:205], v[18:21]
	v_mfma_f32_16x16x32_bf16 v[6:9], v[160:163], v[210:213], v[6:9]
	v_mfma_f32_16x16x32_bf16 v[2:5], v[168:171], v[210:213], v[2:5]
	s_setprio 0
	s_barrier
	s_add_i32 s47, 0, 0x18000
	s_add_i32 s48, 0, 0x1c000
	v_add_u32_e32 v152, s47, v195
	v_add_u32_e32 v168, s48, v195
	ds_read_b128 v[140:143], v152
	ds_read_b128 v[144:147], v152 offset:1024
	ds_read_b128 v[148:151], v152 offset:2048
	ds_read_b128 v[152:155], v152 offset:3072
	ds_read_b128 v[156:159], v168
	ds_read_b128 v[160:163], v168 offset:1024
	ds_read_b128 v[164:167], v168 offset:2048
	ds_read_b128 v[168:171], v168 offset:3072
	s_add_u32 s30, s30, 0x80000
	s_addc_u32 s31, s31, 0
	s_mov_b32 m0, s35
	v_lshl_add_u64 v[220:221], s[30:31], 0, v[130:131]
	ds_read_b128 v[172:175], v199 offset:32768
	ds_read_b128 v[176:179], v199 offset:33792
	ds_read_b128 v[180:183], v199 offset:34816
	ds_read_b128 v[184:187], v199 offset:35840
	ds_read_b128 v[188:191], v199 offset:36864
	ds_read_b128 v[202:205], v199 offset:37888
	ds_read_b128 v[206:209], v199 offset:38912
	ds_read_b128 v[210:213], v199 offset:39936
	global_load_lds_dwordx4 v[220:221], off
	v_lshl_add_u64 v[220:221], s[30:31], 0, v[132:133]
	s_mov_b32 m0, s36
	s_nop 0
	global_load_lds_dwordx4 v[220:221], off
	s_waitcnt vmcnt(8)
	s_waitcnt lgkmcnt(0)
	s_barrier
	s_setprio 1
	v_mfma_f32_16x16x32_bf16 v[126:129], v[140:143], v[172:175], v[126:129]
	v_mfma_f32_16x16x32_bf16 v[122:125], v[148:151], v[172:175], v[122:125]
	v_mfma_f32_16x16x32_bf16 v[110:113], v[140:143], v[180:183], v[110:113]
	v_mfma_f32_16x16x32_bf16 v[106:109], v[148:151], v[180:183], v[106:109]
	v_mfma_f32_16x16x32_bf16 v[94:97], v[140:143], v[188:191], v[94:97]
	v_mfma_f32_16x16x32_bf16 v[90:93], v[148:151], v[188:191], v[90:93]
	v_mfma_f32_16x16x32_bf16 v[78:81], v[140:143], v[206:209], v[78:81]
	v_mfma_f32_16x16x32_bf16 v[74:77], v[148:151], v[206:209], v[74:77]
	v_mfma_f32_16x16x32_bf16 v[126:129], v[144:147], v[176:179], v[126:129]
	v_mfma_f32_16x16x32_bf16 v[122:125], v[152:155], v[176:179], v[122:125]
	v_mfma_f32_16x16x32_bf16 v[110:113], v[144:147], v[184:187], v[110:113]
	v_mfma_f32_16x16x32_bf16 v[106:109], v[152:155], v[184:187], v[106:109]
	v_mfma_f32_16x16x32_bf16 v[94:97], v[144:147], v[202:205], v[94:97]
	v_mfma_f32_16x16x32_bf16 v[90:93], v[152:155], v[202:205], v[90:93]
	v_mfma_f32_16x16x32_bf16 v[78:81], v[144:147], v[210:213], v[78:81]
	v_mfma_f32_16x16x32_bf16 v[74:77], v[152:155], v[210:213], v[74:77]
	v_mfma_f32_16x16x32_bf16 v[118:121], v[156:159], v[172:175], v[118:121]
	v_mfma_f32_16x16x32_bf16 v[114:117], v[164:167], v[172:175], v[114:117]
	v_mfma_f32_16x16x32_bf16 v[102:105], v[156:159], v[180:183], v[102:105]
	v_mfma_f32_16x16x32_bf16 v[98:101], v[164:167], v[180:183], v[98:101]
	v_mfma_f32_16x16x32_bf16 v[86:89], v[156:159], v[188:191], v[86:89]
	v_mfma_f32_16x16x32_bf16 v[82:85], v[164:167], v[188:191], v[82:85]
	v_mfma_f32_16x16x32_bf16 v[70:73], v[156:159], v[206:209], v[70:73]
	v_mfma_f32_16x16x32_bf16 v[66:69], v[164:167], v[206:209], v[66:69]
	v_mfma_f32_16x16x32_bf16 v[118:121], v[160:163], v[176:179], v[118:121]
	v_mfma_f32_16x16x32_bf16 v[114:117], v[168:171], v[176:179], v[114:117]
	v_mfma_f32_16x16x32_bf16 v[102:105], v[160:163], v[184:187], v[102:105]
	v_mfma_f32_16x16x32_bf16 v[98:101], v[168:171], v[184:187], v[98:101]
	v_mfma_f32_16x16x32_bf16 v[86:89], v[160:163], v[202:205], v[86:89]
	v_mfma_f32_16x16x32_bf16 v[82:85], v[168:171], v[202:205], v[82:85]
	v_mfma_f32_16x16x32_bf16 v[70:73], v[160:163], v[210:213], v[70:73]
	v_mfma_f32_16x16x32_bf16 v[66:69], v[168:171], v[210:213], v[66:69]
	s_setprio 0
	s_barrier
	s_add_i32 s30, s47, s3
	v_lshl_add_u64 v[192:193], v[192:193], 0, s[8:9]
	s_mov_b32 m0, s30
	ds_read_b128 v[172:175], v199 offset:49152
	ds_read_b128 v[176:179], v199 offset:50176
	ds_read_b128 v[180:183], v199 offset:51200
	ds_read_b128 v[184:187], v199 offset:52224
	ds_read_b128 v[188:191], v199 offset:53248
	ds_read_b128 v[202:205], v199 offset:54272
	ds_read_b128 v[206:209], v199 offset:55296
	ds_read_b128 v[210:213], v199 offset:56320
	global_load_lds_dwordx4 v[192:193], off
	s_add_i32 m0, s30, 0x2000
	s_add_u32 s28, s28, 0x80080
	v_lshl_add_u64 v[192:193], v[214:215], 0, s[8:9]
	s_addc_u32 s29, s29, 0
	s_add_i32 s30, s48, s3
	global_load_lds_dwordx4 v[192:193], off
	v_lshl_add_u64 v[192:193], s[28:29], 0, v[130:131]
	s_mov_b32 m0, s30
	s_nop 0
	global_load_lds_dwordx4 v[192:193], off
	v_lshl_add_u64 v[192:193], s[28:29], 0, v[132:133]
	s_add_i32 m0, s30, 0x2000
	s_nop 0
	global_load_lds_dwordx4 v[192:193], off
	v_lshl_add_u64 v[192:193], v[216:217], 0, s[8:9]
	s_mov_b32 m0, s38
	s_nop 0
	global_load_lds_dwordx4 v[192:193], off
	v_lshl_add_u64 v[192:193], v[218:219], 0, s[8:9]
	s_mov_b32 m0, s39
	s_nop 0
	global_load_lds_dwordx4 v[192:193], off
	s_waitcnt vmcnt(8)
	s_waitcnt lgkmcnt(0)
	s_barrier
	s_setprio 1
	v_mfma_f32_16x16x32_bf16 v[62:65], v[140:143], v[172:175], v[62:65]
	v_mfma_f32_16x16x32_bf16 v[58:61], v[148:151], v[172:175], v[58:61]
	v_mfma_f32_16x16x32_bf16 v[46:49], v[140:143], v[180:183], v[46:49]
	v_mfma_f32_16x16x32_bf16 v[42:45], v[148:151], v[180:183], v[42:45]
	v_mfma_f32_16x16x32_bf16 v[30:33], v[140:143], v[188:191], v[30:33]
	v_mfma_f32_16x16x32_bf16 v[26:29], v[148:151], v[188:191], v[26:29]
	v_mfma_f32_16x16x32_bf16 v[14:17], v[140:143], v[206:209], v[14:17]
	v_mfma_f32_16x16x32_bf16 v[10:13], v[148:151], v[206:209], v[10:13]
	v_mfma_f32_16x16x32_bf16 v[62:65], v[144:147], v[176:179], v[62:65]
	v_mfma_f32_16x16x32_bf16 v[58:61], v[152:155], v[176:179], v[58:61]
	v_mfma_f32_16x16x32_bf16 v[46:49], v[144:147], v[184:187], v[46:49]
	v_mfma_f32_16x16x32_bf16 v[42:45], v[152:155], v[184:187], v[42:45]
	v_mfma_f32_16x16x32_bf16 v[30:33], v[144:147], v[202:205], v[30:33]
	v_mfma_f32_16x16x32_bf16 v[26:29], v[152:155], v[202:205], v[26:29]
	v_mfma_f32_16x16x32_bf16 v[14:17], v[144:147], v[210:213], v[14:17]
	v_mfma_f32_16x16x32_bf16 v[10:13], v[152:155], v[210:213], v[10:13]
	v_mfma_f32_16x16x32_bf16 v[54:57], v[156:159], v[172:175], v[54:57]
	v_mfma_f32_16x16x32_bf16 v[50:53], v[164:167], v[172:175], v[50:53]
	v_mfma_f32_16x16x32_bf16 v[38:41], v[156:159], v[180:183], v[38:41]
	v_mfma_f32_16x16x32_bf16 v[34:37], v[164:167], v[180:183], v[34:37]
	v_mfma_f32_16x16x32_bf16 v[22:25], v[156:159], v[188:191], v[22:25]
	v_mfma_f32_16x16x32_bf16 v[18:21], v[164:167], v[188:191], v[18:21]
	v_mfma_f32_16x16x32_bf16 v[6:9], v[156:159], v[206:209], v[6:9]
	v_mfma_f32_16x16x32_bf16 v[2:5], v[164:167], v[206:209], v[2:5]
	v_mfma_f32_16x16x32_bf16 v[54:57], v[160:163], v[176:179], v[54:57]
	v_mfma_f32_16x16x32_bf16 v[50:53], v[168:171], v[176:179], v[50:53]
	v_mfma_f32_16x16x32_bf16 v[38:41], v[160:163], v[184:187], v[38:41]
	v_mfma_f32_16x16x32_bf16 v[34:37], v[168:171], v[184:187], v[34:37]
	v_mfma_f32_16x16x32_bf16 v[22:25], v[160:163], v[202:205], v[22:25]
	v_mfma_f32_16x16x32_bf16 v[18:21], v[168:171], v[202:205], v[18:21]
	v_mfma_f32_16x16x32_bf16 v[6:9], v[160:163], v[210:213], v[6:9]
	v_mfma_f32_16x16x32_bf16 v[2:5], v[168:171], v[210:213], v[2:5]
	s_setprio 0
	s_barrier
	s_add_i32 s46, s46, 2
	s_add_u32 s44, s44, 0x100
	s_addc_u32 s45, s45, 0
	s_add_u32 s26, s26, 0x100
	s_addc_u32 s27, s27, 0
	s_cmp_gt_u32 s46, 29
	s_cbranch_scc0 .LBB0_651
	s_and_b64 vcc, exec, s[10:11]
	s_cbranch_vccz .LBB0_654
	s_barrier

.LBB0_808:
	ds_read_b128 v[144:147], v152
	ds_read_b128 v[156:159], v152 offset:1024
	ds_read_b128 v[160:163], v152 offset:2048
	ds_read_b128 v[164:167], v152 offset:3072
	ds_read_b128 v[168:171], v153
	ds_read_b128 v[172:175], v153 offset:1024
	ds_read_b128 v[176:179], v153 offset:2048
	ds_read_b128 v[180:183], v153 offset:3072
	s_add_u32 s34, s30, 0xfff80080
	s_addc_u32 s35, s31, -1
	s_cmp_eq_u32 s55, 28
	s_cselect_b32 s37, s19, s35
	s_cselect_b32 s36, s51, s34
	s_cselect_b32 s35, s17, s54
	s_cselect_b32 s34, s52, s53
	v_lshl_add_u64 v[148:149], s[30:31], 0, v[138:139]
	s_add_i32 m0, s27, 0xc000
	ds_read_b128 v[184:187], v154
	ds_read_b128 v[188:191], v154 offset:1024
	ds_read_b128 v[196:199], v154 offset:2048
	ds_read_b128 v[200:203], v154 offset:3072
	ds_read_b128 v[204:207], v154 offset:4096
	ds_read_b128 v[208:211], v154 offset:5120
	ds_read_b128 v[212:215], v154 offset:6144
	ds_read_b128 v[216:219], v154 offset:7168
	global_load_lds_dwordx4 v[148:149], off
	v_lshl_add_u64 v[148:149], s[30:31], 0, v[140:141]
	s_add_i32 m0, s27, 0xe000
	s_nop 0
	global_load_lds_dwordx4 v[148:149], off
	s_waitcnt vmcnt(8)
	s_waitcnt lgkmcnt(0)
	s_barrier
	s_setprio 1
	v_mfma_f32_16x16x32_bf16 v[126:129], v[144:147], v[184:187], v[126:129]
	v_mfma_f32_16x16x32_bf16 v[122:125], v[160:163], v[184:187], v[122:125]
	v_mfma_f32_16x16x32_bf16 v[110:113], v[144:147], v[196:199], v[110:113]
	v_mfma_f32_16x16x32_bf16 v[106:109], v[160:163], v[196:199], v[106:109]
	v_mfma_f32_16x16x32_bf16 v[94:97], v[144:147], v[204:207], v[94:97]
	v_mfma_f32_16x16x32_bf16 v[90:93], v[160:163], v[204:207], v[90:93]
	v_mfma_f32_16x16x32_bf16 v[78:81], v[144:147], v[212:215], v[78:81]
	v_mfma_f32_16x16x32_bf16 v[74:77], v[160:163], v[212:215], v[74:77]
	v_mfma_f32_16x16x32_bf16 v[126:129], v[156:159], v[188:191], v[126:129]
	v_mfma_f32_16x16x32_bf16 v[122:125], v[164:167], v[188:191], v[122:125]
	v_mfma_f32_16x16x32_bf16 v[110:113], v[156:159], v[200:203], v[110:113]
	v_mfma_f32_16x16x32_bf16 v[106:109], v[164:167], v[200:203], v[106:109]
	v_mfma_f32_16x16x32_bf16 v[94:97], v[156:159], v[208:211], v[94:97]
	v_mfma_f32_16x16x32_bf16 v[90:93], v[164:167], v[208:211], v[90:93]
	v_mfma_f32_16x16x32_bf16 v[78:81], v[156:159], v[216:219], v[78:81]
	v_mfma_f32_16x16x32_bf16 v[74:77], v[164:167], v[216:219], v[74:77]
	v_mfma_f32_16x16x32_bf16 v[118:121], v[168:171], v[184:187], v[118:121]
	v_mfma_f32_16x16x32_bf16 v[114:117], v[176:179], v[184:187], v[114:117]
	v_mfma_f32_16x16x32_bf16 v[102:105], v[168:171], v[196:199], v[102:105]
	v_mfma_f32_16x16x32_bf16 v[98:101], v[176:179], v[196:199], v[98:101]
	v_mfma_f32_16x16x32_bf16 v[86:89], v[168:171], v[204:207], v[86:89]
	v_mfma_f32_16x16x32_bf16 v[82:85], v[176:179], v[204:207], v[82:85]
	v_mfma_f32_16x16x32_bf16 v[70:73], v[168:171], v[212:215], v[70:73]
	v_mfma_f32_16x16x32_bf16 v[66:69], v[176:179], v[212:215], v[66:69]
	v_mfma_f32_16x16x32_bf16 v[118:121], v[172:175], v[188:191], v[118:121]
	v_mfma_f32_16x16x32_bf16 v[114:117], v[180:183], v[188:191], v[114:117]
	v_mfma_f32_16x16x32_bf16 v[102:105], v[172:175], v[200:203], v[102:105]
	v_mfma_f32_16x16x32_bf16 v[98:101], v[180:183], v[200:203], v[98:101]
	v_mfma_f32_16x16x32_bf16 v[86:89], v[172:175], v[208:211], v[86:89]
	v_mfma_f32_16x16x32_bf16 v[82:85], v[180:183], v[208:211], v[82:85]
	v_mfma_f32_16x16x32_bf16 v[70:73], v[172:175], v[216:219], v[70:73]
	v_mfma_f32_16x16x32_bf16 v[66:69], v[180:183], v[216:219], v[66:69]
	s_setprio 0
	s_barrier
	s_add_i32 s56, s47, s38
	v_lshl_add_u64 v[148:149], s[34:35], 0, v[132:133]
	s_mov_b32 m0, s56
	ds_read_b128 v[184:187], v154 offset:16384
	ds_read_b128 v[188:191], v154 offset:17408
	ds_read_b128 v[196:199], v154 offset:18432
	ds_read_b128 v[200:203], v154 offset:19456
	ds_read_b128 v[204:207], v154 offset:20480
	ds_read_b128 v[208:211], v154 offset:21504
	ds_read_b128 v[212:215], v154 offset:22528
	ds_read_b128 v[216:219], v154 offset:23552
	global_load_lds_dwordx4 v[148:149], off
	s_add_i32 m0, s56, 0x2000
	s_add_u32 s56, s34, 0x80000
	v_lshl_add_u64 v[192:193], s[34:35], 0, v[136:137]
	s_addc_u32 s57, s35, 0
	s_add_i32 s58, s48, s38
	global_load_lds_dwordx4 v[192:193], off
	v_lshl_add_u64 v[220:221], s[56:57], 0, v[132:133]
	s_mov_b32 m0, s58
	v_lshl_add_u64 v[222:223], s[36:37], 0, v[134:135]
	global_load_lds_dwordx4 v[220:221], off
	v_lshl_add_u64 v[220:221], s[56:57], 0, v[136:137]
	s_add_i32 m0, s58, 0x2000
	s_nop 0
	global_load_lds_dwordx4 v[220:221], off
	v_lshl_add_u64 v[220:221], s[36:37], 0, v[130:131]
	s_mov_b32 m0, s27
	s_nop 0
	global_load_lds_dwordx4 v[220:221], off
	s_mov_b32 m0, s29
	s_nop 0
	global_load_lds_dwordx4 v[222:223], off
	s_waitcnt vmcnt(8)
	s_waitcnt lgkmcnt(0)
	s_barrier
	s_setprio 1
	v_mfma_f32_16x16x32_bf16 v[62:65], v[144:147], v[184:187], v[62:65]
	v_mfma_f32_16x16x32_bf16 v[58:61], v[160:163], v[184:187], v[58:61]
	v_mfma_f32_16x16x32_bf16 v[46:49], v[144:147], v[196:199], v[46:49]
	v_mfma_f32_16x16x32_bf16 v[42:45], v[160:163], v[196:199], v[42:45]
	v_mfma_f32_16x16x32_bf16 v[30:33], v[144:147], v[204:207], v[30:33]
	v_mfma_f32_16x16x32_bf16 v[26:29], v[160:163], v[204:207], v[26:29]
	v_mfma_f32_16x16x32_bf16 v[14:17], v[144:147], v[212:215], v[14:17]
	v_mfma_f32_16x16x32_bf16 v[10:13], v[160:163], v[212:215], v[10:13]
	v_mfma_f32_16x16x32_bf16 v[62:65], v[156:159], v[188:191], v[62:65]
	v_mfma_f32_16x16x32_bf16 v[58:61], v[164:167], v[188:191], v[58:61]
	v_mfma_f32_16x16x32_bf16 v[46:49], v[156:159], v[200:203], v[46:49]
	v_mfma_f32_16x16x32_bf16 v[42:45], v[164:167], v[200:203], v[42:45]
	v_mfma_f32_16x16x32_bf16 v[30:33], v[156:159], v[208:211], v[30:33]
	v_mfma_f32_16x16x32_bf16 v[26:29], v[164:167], v[208:211], v[26:29]
	v_mfma_f32_16x16x32_bf16 v[14:17], v[156:159], v[216:219], v[14:17]
	v_mfma_f32_16x16x32_bf16 v[10:13], v[164:167], v[216:219], v[10:13]
	v_mfma_f32_16x16x32_bf16 v[54:57], v[168:171], v[184:187], v[54:57]
	v_mfma_f32_16x16x32_bf16 v[50:53], v[176:179], v[184:187], v[50:53]
	v_mfma_f32_16x16x32_bf16 v[38:41], v[168:171], v[196:199], v[38:41]
	v_mfma_f32_16x16x32_bf16 v[34:37], v[176:179], v[196:199], v[34:37]
	v_mfma_f32_16x16x32_bf16 v[22:25], v[168:171], v[204:207], v[22:25]
	v_mfma_f32_16x16x32_bf16 v[18:21], v[176:179], v[204:207], v[18:21]
	v_mfma_f32_16x16x32_bf16 v[6:9], v[168:171], v[212:215], v[6:9]
	v_mfma_f32_16x16x32_bf16 v[2:5], v[176:179], v[212:215], v[2:5]
	v_mfma_f32_16x16x32_bf16 v[54:57], v[172:175], v[188:191], v[54:57]
	v_mfma_f32_16x16x32_bf16 v[50:53], v[180:183], v[188:191], v[50:53]
	v_mfma_f32_16x16x32_bf16 v[38:41], v[172:175], v[200:203], v[38:41]
	v_mfma_f32_16x16x32_bf16 v[34:37], v[180:183], v[200:203], v[34:37]
	v_mfma_f32_16x16x32_bf16 v[22:25], v[172:175], v[208:211], v[22:25]
	v_mfma_f32_16x16x32_bf16 v[18:21], v[180:183], v[208:211], v[18:21]
	v_mfma_f32_16x16x32_bf16 v[6:9], v[172:175], v[216:219], v[6:9]
	v_mfma_f32_16x16x32_bf16 v[2:5], v[180:183], v[216:219], v[2:5]
	s_setprio 0
	s_barrier
	s_add_i32 s56, 0, 0x18000
	v_add_u32_e32 v155, s56, v150
	s_add_i32 s57, 0, 0x1c000
	ds_read_b128 v[144:147], v155
	ds_read_b128 v[156:159], v155 offset:1024
	ds_read_b128 v[160:163], v155 offset:2048
	ds_read_b128 v[164:167], v155 offset:3072
	v_add_u32_e32 v155, s57, v150
	ds_read_b128 v[168:171], v155
	ds_read_b128 v[172:175], v155 offset:1024
	ds_read_b128 v[176:179], v155 offset:2048
	ds_read_b128 v[180:183], v155 offset:3072
	s_add_u32 s36, s36, 0x80000
	s_addc_u32 s37, s37, 0
	s_mov_b32 m0, s39
	v_lshl_add_u64 v[224:225], s[36:37], 0, v[130:131]
	ds_read_b128 v[184:187], v154 offset:32768
	ds_read_b128 v[188:191], v154 offset:33792
	ds_read_b128 v[196:199], v154 offset:34816
	ds_read_b128 v[200:203], v154 offset:35840
	ds_read_b128 v[204:207], v154 offset:36864
	ds_read_b128 v[208:211], v154 offset:37888
	ds_read_b128 v[212:215], v154 offset:38912
	ds_read_b128 v[216:219], v154 offset:39936
	global_load_lds_dwordx4 v[224:225], off
	v_lshl_add_u64 v[224:225], s[36:37], 0, v[134:135]
	s_mov_b32 m0, s40
	s_nop 0
	global_load_lds_dwordx4 v[224:225], off
	s_waitcnt vmcnt(8)
	s_waitcnt lgkmcnt(0)
	s_barrier
	s_setprio 1
	v_mfma_f32_16x16x32_bf16 v[126:129], v[144:147], v[184:187], v[126:129]
	v_mfma_f32_16x16x32_bf16 v[122:125], v[160:163], v[184:187], v[122:125]
	v_mfma_f32_16x16x32_bf16 v[110:113], v[144:147], v[196:199], v[110:113]
	v_mfma_f32_16x16x32_bf16 v[106:109], v[160:163], v[196:199], v[106:109]
	v_mfma_f32_16x16x32_bf16 v[94:97], v[144:147], v[204:207], v[94:97]
	v_mfma_f32_16x16x32_bf16 v[90:93], v[160:163], v[204:207], v[90:93]
	v_mfma_f32_16x16x32_bf16 v[78:81], v[144:147], v[212:215], v[78:81]
	v_mfma_f32_16x16x32_bf16 v[74:77], v[160:163], v[212:215], v[74:77]
	v_mfma_f32_16x16x32_bf16 v[126:129], v[156:159], v[188:191], v[126:129]
	v_mfma_f32_16x16x32_bf16 v[122:125], v[164:167], v[188:191], v[122:125]
	v_mfma_f32_16x16x32_bf16 v[110:113], v[156:159], v[200:203], v[110:113]
	v_mfma_f32_16x16x32_bf16 v[106:109], v[164:167], v[200:203], v[106:109]
	v_mfma_f32_16x16x32_bf16 v[94:97], v[156:159], v[208:211], v[94:97]
	v_mfma_f32_16x16x32_bf16 v[90:93], v[164:167], v[208:211], v[90:93]
	v_mfma_f32_16x16x32_bf16 v[78:81], v[156:159], v[216:219], v[78:81]
	v_mfma_f32_16x16x32_bf16 v[74:77], v[164:167], v[216:219], v[74:77]
	v_mfma_f32_16x16x32_bf16 v[118:121], v[168:171], v[184:187], v[118:121]
	v_mfma_f32_16x16x32_bf16 v[114:117], v[176:179], v[184:187], v[114:117]
	v_mfma_f32_16x16x32_bf16 v[102:105], v[168:171], v[196:199], v[102:105]
	v_mfma_f32_16x16x32_bf16 v[98:101], v[176:179], v[196:199], v[98:101]
	v_mfma_f32_16x16x32_bf16 v[86:89], v[168:171], v[204:207], v[86:89]
	v_mfma_f32_16x16x32_bf16 v[82:85], v[176:179], v[204:207], v[82:85]
	v_mfma_f32_16x16x32_bf16 v[70:73], v[168:171], v[212:215], v[70:73]
	v_mfma_f32_16x16x32_bf16 v[66:69], v[176:179], v[212:215], v[66:69]
	v_mfma_f32_16x16x32_bf16 v[118:121], v[172:175], v[188:191], v[118:121]
	v_mfma_f32_16x16x32_bf16 v[114:117], v[180:183], v[188:191], v[114:117]
	v_mfma_f32_16x16x32_bf16 v[102:105], v[172:175], v[200:203], v[102:105]
	v_mfma_f32_16x16x32_bf16 v[98:101], v[180:183], v[200:203], v[98:101]
	v_mfma_f32_16x16x32_bf16 v[86:89], v[172:175], v[208:211], v[86:89]
	v_mfma_f32_16x16x32_bf16 v[82:85], v[180:183], v[208:211], v[82:85]
	v_mfma_f32_16x16x32_bf16 v[70:73], v[172:175], v[216:219], v[70:73]
	v_mfma_f32_16x16x32_bf16 v[66:69], v[180:183], v[216:219], v[66:69]
	s_setprio 0
	s_barrier
	s_add_i32 s36, s56, s38
	v_lshl_add_u64 v[148:149], v[148:149], 0, s[10:11]
	s_mov_b32 m0, s36
	ds_read_b128 v[184:187], v154 offset:49152
	ds_read_b128 v[188:191], v154 offset:50176
	ds_read_b128 v[196:199], v154 offset:51200
	ds_read_b128 v[200:203], v154 offset:52224
	ds_read_b128 v[204:207], v154 offset:53248
	ds_read_b128 v[208:211], v154 offset:54272
	ds_read_b128 v[212:215], v154 offset:55296
	ds_read_b128 v[216:219], v154 offset:56320
	global_load_lds_dwordx4 v[148:149], off
	s_add_i32 m0, s36, 0x2000
	s_add_u32 s34, s34, 0x80080
	v_lshl_add_u64 v[148:149], v[192:193], 0, s[10:11]
	s_addc_u32 s35, s35, 0
	s_add_i32 s36, s57, s38
	global_load_lds_dwordx4 v[148:149], off
	v_lshl_add_u64 v[148:149], s[34:35], 0, v[132:133]
	s_mov_b32 m0, s36
	s_nop 0
	global_load_lds_dwordx4 v[148:149], off
	v_lshl_add_u64 v[148:149], s[34:35], 0, v[136:137]
	s_add_i32 m0, s36, 0x2000
	s_nop 0
	global_load_lds_dwordx4 v[148:149], off
	v_lshl_add_u64 v[148:149], v[220:221], 0, s[10:11]
	s_mov_b32 m0, s42
	s_nop 0
	global_load_lds_dwordx4 v[148:149], off
	v_lshl_add_u64 v[148:149], v[222:223], 0, s[10:11]
	s_mov_b32 m0, s43
	s_nop 0
	global_load_lds_dwordx4 v[148:149], off
	s_waitcnt vmcnt(8)
	s_waitcnt lgkmcnt(0)
	s_barrier
	s_setprio 1
	v_mfma_f32_16x16x32_bf16 v[62:65], v[144:147], v[184:187], v[62:65]
	v_mfma_f32_16x16x32_bf16 v[58:61], v[160:163], v[184:187], v[58:61]
	v_mfma_f32_16x16x32_bf16 v[46:49], v[144:147], v[196:199], v[46:49]
	v_mfma_f32_16x16x32_bf16 v[42:45], v[160:163], v[196:199], v[42:45]
	v_mfma_f32_16x16x32_bf16 v[30:33], v[144:147], v[204:207], v[30:33]
	v_mfma_f32_16x16x32_bf16 v[26:29], v[160:163], v[204:207], v[26:29]
	v_mfma_f32_16x16x32_bf16 v[14:17], v[144:147], v[212:215], v[14:17]
	v_mfma_f32_16x16x32_bf16 v[10:13], v[160:163], v[212:215], v[10:13]
	v_mfma_f32_16x16x32_bf16 v[62:65], v[156:159], v[188:191], v[62:65]
	v_mfma_f32_16x16x32_bf16 v[58:61], v[164:167], v[188:191], v[58:61]
	v_mfma_f32_16x16x32_bf16 v[46:49], v[156:159], v[200:203], v[46:49]
	v_mfma_f32_16x16x32_bf16 v[42:45], v[164:167], v[200:203], v[42:45]
	v_mfma_f32_16x16x32_bf16 v[30:33], v[156:159], v[208:211], v[30:33]
	v_mfma_f32_16x16x32_bf16 v[26:29], v[164:167], v[208:211], v[26:29]
	v_mfma_f32_16x16x32_bf16 v[14:17], v[156:159], v[216:219], v[14:17]
	v_mfma_f32_16x16x32_bf16 v[10:13], v[164:167], v[216:219], v[10:13]
	v_mfma_f32_16x16x32_bf16 v[54:57], v[168:171], v[184:187], v[54:57]
	v_mfma_f32_16x16x32_bf16 v[50:53], v[176:179], v[184:187], v[50:53]
	v_mfma_f32_16x16x32_bf16 v[38:41], v[168:171], v[196:199], v[38:41]
	v_mfma_f32_16x16x32_bf16 v[34:37], v[176:179], v[196:199], v[34:37]
	v_mfma_f32_16x16x32_bf16 v[22:25], v[168:171], v[204:207], v[22:25]
	v_mfma_f32_16x16x32_bf16 v[18:21], v[176:179], v[204:207], v[18:21]
	v_mfma_f32_16x16x32_bf16 v[6:9], v[168:171], v[212:215], v[6:9]
	v_mfma_f32_16x16x32_bf16 v[2:5], v[176:179], v[212:215], v[2:5]
	v_mfma_f32_16x16x32_bf16 v[54:57], v[172:175], v[188:191], v[54:57]
	v_mfma_f32_16x16x32_bf16 v[50:53], v[180:183], v[188:191], v[50:53]
	v_mfma_f32_16x16x32_bf16 v[38:41], v[172:175], v[200:203], v[38:41]
	v_mfma_f32_16x16x32_bf16 v[34:37], v[180:183], v[200:203], v[34:37]
	v_mfma_f32_16x16x32_bf16 v[22:25], v[172:175], v[208:211], v[22:25]
	v_mfma_f32_16x16x32_bf16 v[18:21], v[180:183], v[208:211], v[18:21]
	v_mfma_f32_16x16x32_bf16 v[6:9], v[172:175], v[216:219], v[6:9]
	v_mfma_f32_16x16x32_bf16 v[2:5], v[180:183], v[216:219], v[2:5]
	s_setprio 0
	s_barrier
	s_add_i32 s55, s55, 2
	s_add_u32 s53, s53, 0x100
	s_addc_u32 s54, s54, 0
	s_add_u32 s30, s30, 0x100
	s_addc_u32 s31, s31, 0
	s_cmp_gt_u32 s55, 29
	s_cbranch_scc0 .LBB0_808
	s_and_b64 vcc, exec, s[12:13]
	s_cbranch_vccz .LBB0_811
	s_barrier

.LBB0_1031:
	ds_read_b128 v[144:147], v139
	ds_read_b128 v[148:151], v139 offset:1024
	ds_read_b128 v[152:155], v139 offset:2048
	ds_read_b128 v[156:159], v139 offset:3072
	ds_read_b128 v[164:167], v140
	ds_read_b128 v[168:171], v140 offset:1024
	ds_read_b128 v[172:175], v140 offset:2048
	ds_read_b128 v[176:179], v140 offset:3072
	s_add_u32 s12, s8, s10
	s_addc_u32 s13, s9, s11
	s_add_u32 s12, s12, 0x2000100
	s_addc_u32 s13, s13, 0
	s_add_u32 s42, s27, s10
	s_addc_u32 s43, s28, s11
	s_cmpk_eq_i32 s10, 0x3f00
	s_cselect_b32 s15, s3, s13
	s_cselect_b32 s14, s2, s12
	s_cselect_b32 s13, s1, s43
	s_cselect_b32 s12, s0, s42
	s_mov_b32 m0, s30
	v_lshl_add_u64 v[160:161], v[134:135], 0, s[10:11]
	ds_read_b128 v[180:183], v141
	ds_read_b128 v[184:187], v141 offset:1024
	ds_read_b128 v[188:191], v141 offset:2048
	ds_read_b128 v[196:199], v141 offset:3072
	ds_read_b128 v[200:203], v141 offset:4096
	ds_read_b128 v[204:207], v141 offset:5120
	ds_read_b128 v[208:211], v141 offset:6144
	ds_read_b128 v[212:215], v141 offset:7168
	global_load_lds_dwordx4 v[160:161], off
	v_lshl_add_u64 v[160:161], v[136:137], 0, s[10:11]
	s_mov_b32 m0, s31
	s_nop 0
	global_load_lds_dwordx4 v[160:161], off
	s_waitcnt vmcnt(8)
	s_waitcnt lgkmcnt(0)
	s_barrier
	s_setprio 1
	v_mfma_f32_16x16x32_bf16 v[126:129], v[144:147], v[180:183], v[126:129]
	v_mfma_f32_16x16x32_bf16 v[122:125], v[152:155], v[180:183], v[122:125]
	v_mfma_f32_16x16x32_bf16 v[110:113], v[144:147], v[188:191], v[110:113]
	v_mfma_f32_16x16x32_bf16 v[106:109], v[152:155], v[188:191], v[106:109]
	v_mfma_f32_16x16x32_bf16 v[94:97], v[144:147], v[200:203], v[94:97]
	v_mfma_f32_16x16x32_bf16 v[90:93], v[152:155], v[200:203], v[90:93]
	v_mfma_f32_16x16x32_bf16 v[78:81], v[144:147], v[208:211], v[78:81]
	v_mfma_f32_16x16x32_bf16 v[74:77], v[152:155], v[208:211], v[74:77]
	v_mfma_f32_16x16x32_bf16 v[126:129], v[148:151], v[184:187], v[126:129]
	v_mfma_f32_16x16x32_bf16 v[122:125], v[156:159], v[184:187], v[122:125]
	v_mfma_f32_16x16x32_bf16 v[110:113], v[148:151], v[196:199], v[110:113]
	v_mfma_f32_16x16x32_bf16 v[106:109], v[156:159], v[196:199], v[106:109]
	v_mfma_f32_16x16x32_bf16 v[94:97], v[148:151], v[204:207], v[94:97]
	v_mfma_f32_16x16x32_bf16 v[90:93], v[156:159], v[204:207], v[90:93]
	v_mfma_f32_16x16x32_bf16 v[78:81], v[148:151], v[212:215], v[78:81]
	v_mfma_f32_16x16x32_bf16 v[74:77], v[156:159], v[212:215], v[74:77]
	v_mfma_f32_16x16x32_bf16 v[118:121], v[164:167], v[180:183], v[118:121]
	v_mfma_f32_16x16x32_bf16 v[114:117], v[172:175], v[180:183], v[114:117]
	v_mfma_f32_16x16x32_bf16 v[102:105], v[164:167], v[188:191], v[102:105]
	v_mfma_f32_16x16x32_bf16 v[98:101], v[172:175], v[188:191], v[98:101]
	v_mfma_f32_16x16x32_bf16 v[86:89], v[164:167], v[200:203], v[86:89]
	v_mfma_f32_16x16x32_bf16 v[82:85], v[172:175], v[200:203], v[82:85]
	v_mfma_f32_16x16x32_bf16 v[70:73], v[164:167], v[208:211], v[70:73]
	v_mfma_f32_16x16x32_bf16 v[66:69], v[172:175], v[208:211], v[66:69]
	v_mfma_f32_16x16x32_bf16 v[118:121], v[168:171], v[184:187], v[118:121]
	v_mfma_f32_16x16x32_bf16 v[114:117], v[176:179], v[184:187], v[114:117]
	v_mfma_f32_16x16x32_bf16 v[102:105], v[168:171], v[196:199], v[102:105]
	v_mfma_f32_16x16x32_bf16 v[98:101], v[176:179], v[196:199], v[98:101]
	v_mfma_f32_16x16x32_bf16 v[86:89], v[168:171], v[204:207], v[86:89]
	v_mfma_f32_16x16x32_bf16 v[82:85], v[176:179], v[204:207], v[82:85]
	v_mfma_f32_16x16x32_bf16 v[70:73], v[168:171], v[212:215], v[70:73]
	v_mfma_f32_16x16x32_bf16 v[66:69], v[176:179], v[212:215], v[66:69]
	s_setprio 0
	s_barrier
	s_mov_b32 m0, s34
	v_lshl_add_u64 v[160:161], s[12:13], 0, v[130:131]
	s_add_u32 s42, s12, 0x200000
	ds_read_b128 v[180:183], v141 offset:16384
	ds_read_b128 v[184:187], v141 offset:17408
	ds_read_b128 v[188:191], v141 offset:18432
	ds_read_b128 v[196:199], v141 offset:19456
	ds_read_b128 v[200:203], v141 offset:20480
	ds_read_b128 v[204:207], v141 offset:21504
	ds_read_b128 v[208:211], v141 offset:22528
	ds_read_b128 v[212:215], v141 offset:23552
	global_load_lds_dwordx4 v[160:161], off
	v_lshl_add_u64 v[192:193], s[12:13], 0, v[132:133]
	s_mov_b32 m0, s35
	s_addc_u32 s43, s13, 0
	global_load_lds_dwordx4 v[192:193], off
	v_lshl_add_u64 v[216:217], s[42:43], 0, v[130:131]
	s_mov_b32 m0, s36
	v_lshl_add_u64 v[218:219], s[14:15], 0, v[132:133]
	global_load_lds_dwordx4 v[216:217], off
	v_lshl_add_u64 v[216:217], s[42:43], 0, v[132:133]
	s_mov_b32 m0, s37
	s_nop 0
	global_load_lds_dwordx4 v[216:217], off
	v_lshl_add_u64 v[216:217], s[14:15], 0, v[130:131]
	s_mov_b32 m0, s20
	s_nop 0
	global_load_lds_dwordx4 v[216:217], off
	s_mov_b32 m0, s21
	s_nop 0
	global_load_lds_dwordx4 v[218:219], off
	s_waitcnt vmcnt(8)
	s_waitcnt lgkmcnt(0)
	s_barrier
	s_setprio 1
	v_mfma_f32_16x16x32_bf16 v[62:65], v[144:147], v[180:183], v[62:65]
	v_mfma_f32_16x16x32_bf16 v[58:61], v[152:155], v[180:183], v[58:61]
	v_mfma_f32_16x16x32_bf16 v[46:49], v[144:147], v[188:191], v[46:49]
	v_mfma_f32_16x16x32_bf16 v[42:45], v[152:155], v[188:191], v[42:45]
	v_mfma_f32_16x16x32_bf16 v[30:33], v[144:147], v[200:203], v[30:33]
	v_mfma_f32_16x16x32_bf16 v[26:29], v[152:155], v[200:203], v[26:29]
	v_mfma_f32_16x16x32_bf16 v[14:17], v[144:147], v[208:211], v[14:17]
	v_mfma_f32_16x16x32_bf16 v[10:13], v[152:155], v[208:211], v[10:13]
	v_mfma_f32_16x16x32_bf16 v[62:65], v[148:151], v[184:187], v[62:65]
	v_mfma_f32_16x16x32_bf16 v[58:61], v[156:159], v[184:187], v[58:61]
	v_mfma_f32_16x16x32_bf16 v[46:49], v[148:151], v[196:199], v[46:49]
	v_mfma_f32_16x16x32_bf16 v[42:45], v[156:159], v[196:199], v[42:45]
	v_mfma_f32_16x16x32_bf16 v[30:33], v[148:151], v[204:207], v[30:33]
	v_mfma_f32_16x16x32_bf16 v[26:29], v[156:159], v[204:207], v[26:29]
	v_mfma_f32_16x16x32_bf16 v[14:17], v[148:151], v[212:215], v[14:17]
	v_mfma_f32_16x16x32_bf16 v[10:13], v[156:159], v[212:215], v[10:13]
	v_mfma_f32_16x16x32_bf16 v[54:57], v[164:167], v[180:183], v[54:57]
	v_mfma_f32_16x16x32_bf16 v[50:53], v[172:175], v[180:183], v[50:53]
	v_mfma_f32_16x16x32_bf16 v[38:41], v[164:167], v[188:191], v[38:41]
	v_mfma_f32_16x16x32_bf16 v[34:37], v[172:175], v[188:191], v[34:37]
	v_mfma_f32_16x16x32_bf16 v[22:25], v[164:167], v[200:203], v[22:25]
	v_mfma_f32_16x16x32_bf16 v[18:21], v[172:175], v[200:203], v[18:21]
	v_mfma_f32_16x16x32_bf16 v[6:9], v[164:167], v[208:211], v[6:9]
	v_mfma_f32_16x16x32_bf16 v[2:5], v[172:175], v[208:211], v[2:5]
	v_mfma_f32_16x16x32_bf16 v[54:57], v[168:171], v[184:187], v[54:57]
	v_mfma_f32_16x16x32_bf16 v[50:53], v[176:179], v[184:187], v[50:53]
	v_mfma_f32_16x16x32_bf16 v[38:41], v[168:171], v[196:199], v[38:41]
	v_mfma_f32_16x16x32_bf16 v[34:37], v[176:179], v[196:199], v[34:37]
	v_mfma_f32_16x16x32_bf16 v[22:25], v[168:171], v[204:207], v[22:25]
	v_mfma_f32_16x16x32_bf16 v[18:21], v[176:179], v[204:207], v[18:21]
	v_mfma_f32_16x16x32_bf16 v[6:9], v[168:171], v[212:215], v[6:9]
	v_mfma_f32_16x16x32_bf16 v[2:5], v[176:179], v[212:215], v[2:5]
	s_setprio 0
	s_barrier
	ds_read_b128 v[144:147], v142
	ds_read_b128 v[148:151], v142 offset:1024
	ds_read_b128 v[152:155], v142 offset:2048
	ds_read_b128 v[156:159], v142 offset:3072
	ds_read_b128 v[164:167], v143
	ds_read_b128 v[168:171], v143 offset:1024
	ds_read_b128 v[172:175], v143 offset:2048
	ds_read_b128 v[176:179], v143 offset:3072
	s_add_u32 s14, s14, 0x200000
	s_addc_u32 s15, s15, 0
	s_mov_b32 m0, s22
	v_lshl_add_u64 v[220:221], s[14:15], 0, v[130:131]
	ds_read_b128 v[180:183], v141 offset:32768
	ds_read_b128 v[184:187], v141 offset:33792
	ds_read_b128 v[188:191], v141 offset:34816
	ds_read_b128 v[196:199], v141 offset:35840
	ds_read_b128 v[200:203], v141 offset:36864
	ds_read_b128 v[204:207], v141 offset:37888
	ds_read_b128 v[208:211], v141 offset:38912
	ds_read_b128 v[212:215], v141 offset:39936
	global_load_lds_dwordx4 v[220:221], off
	v_lshl_add_u64 v[220:221], s[14:15], 0, v[132:133]
	s_mov_b32 m0, s23
	s_nop 0
	global_load_lds_dwordx4 v[220:221], off
	s_waitcnt vmcnt(8)
	s_waitcnt lgkmcnt(0)
	s_barrier
	s_setprio 1
	v_mfma_f32_16x16x32_bf16 v[126:129], v[144:147], v[180:183], v[126:129]
	v_mfma_f32_16x16x32_bf16 v[122:125], v[152:155], v[180:183], v[122:125]
	v_mfma_f32_16x16x32_bf16 v[110:113], v[144:147], v[188:191], v[110:113]
	v_mfma_f32_16x16x32_bf16 v[106:109], v[152:155], v[188:191], v[106:109]
	v_mfma_f32_16x16x32_bf16 v[94:97], v[144:147], v[200:203], v[94:97]
	v_mfma_f32_16x16x32_bf16 v[90:93], v[152:155], v[200:203], v[90:93]
	v_mfma_f32_16x16x32_bf16 v[78:81], v[144:147], v[208:211], v[78:81]
	v_mfma_f32_16x16x32_bf16 v[74:77], v[152:155], v[208:211], v[74:77]
	v_mfma_f32_16x16x32_bf16 v[126:129], v[148:151], v[184:187], v[126:129]
	v_mfma_f32_16x16x32_bf16 v[122:125], v[156:159], v[184:187], v[122:125]
	v_mfma_f32_16x16x32_bf16 v[110:113], v[148:151], v[196:199], v[110:113]
	v_mfma_f32_16x16x32_bf16 v[106:109], v[156:159], v[196:199], v[106:109]
	v_mfma_f32_16x16x32_bf16 v[94:97], v[148:151], v[204:207], v[94:97]
	v_mfma_f32_16x16x32_bf16 v[90:93], v[156:159], v[204:207], v[90:93]
	v_mfma_f32_16x16x32_bf16 v[78:81], v[148:151], v[212:215], v[78:81]
	v_mfma_f32_16x16x32_bf16 v[74:77], v[156:159], v[212:215], v[74:77]
	v_mfma_f32_16x16x32_bf16 v[118:121], v[164:167], v[180:183], v[118:121]
	v_mfma_f32_16x16x32_bf16 v[114:117], v[172:175], v[180:183], v[114:117]
	v_mfma_f32_16x16x32_bf16 v[102:105], v[164:167], v[188:191], v[102:105]
	v_mfma_f32_16x16x32_bf16 v[98:101], v[172:175], v[188:191], v[98:101]
	v_mfma_f32_16x16x32_bf16 v[86:89], v[164:167], v[200:203], v[86:89]
	v_mfma_f32_16x16x32_bf16 v[82:85], v[172:175], v[200:203], v[82:85]
	v_mfma_f32_16x16x32_bf16 v[70:73], v[164:167], v[208:211], v[70:73]
	v_mfma_f32_16x16x32_bf16 v[66:69], v[172:175], v[208:211], v[66:69]
	v_mfma_f32_16x16x32_bf16 v[118:121], v[168:171], v[184:187], v[118:121]
	v_mfma_f32_16x16x32_bf16 v[114:117], v[176:179], v[184:187], v[114:117]
	v_mfma_f32_16x16x32_bf16 v[102:105], v[168:171], v[196:199], v[102:105]
	v_mfma_f32_16x16x32_bf16 v[98:101], v[176:179], v[196:199], v[98:101]
	v_mfma_f32_16x16x32_bf16 v[86:89], v[168:171], v[204:207], v[86:89]
	v_mfma_f32_16x16x32_bf16 v[82:85], v[176:179], v[204:207], v[82:85]
	v_mfma_f32_16x16x32_bf16 v[70:73], v[168:171], v[212:215], v[70:73]
	v_mfma_f32_16x16x32_bf16 v[66:69], v[176:179], v[212:215], v[66:69]
	s_setprio 0
	s_barrier
	s_mov_b32 m0, s38
	v_lshl_add_u64 v[160:161], v[160:161], 0, s[4:5]
	s_add_u32 s12, s12, 0x200080
	ds_read_b128 v[180:183], v141 offset:49152
	ds_read_b128 v[184:187], v141 offset:50176
	ds_read_b128 v[188:191], v141 offset:51200
	ds_read_b128 v[196:199], v141 offset:52224
	ds_read_b128 v[200:203], v141 offset:53248
	ds_read_b128 v[204:207], v141 offset:54272
	ds_read_b128 v[208:211], v141 offset:55296
	ds_read_b128 v[212:215], v141 offset:56320
	global_load_lds_dwordx4 v[160:161], off
	v_lshl_add_u64 v[160:161], v[192:193], 0, s[4:5]
	s_mov_b32 m0, s39
	s_addc_u32 s13, s13, 0
	global_load_lds_dwordx4 v[160:161], off
	v_lshl_add_u64 v[160:161], s[12:13], 0, v[130:131]
	s_mov_b32 m0, s40
	s_nop 0
	global_load_lds_dwordx4 v[160:161], off
	v_lshl_add_u64 v[160:161], s[12:13], 0, v[132:133]
	s_mov_b32 m0, s41
	s_nop 0
	global_load_lds_dwordx4 v[160:161], off
	v_lshl_add_u64 v[160:161], v[216:217], 0, s[4:5]
	s_mov_b32 m0, s25
	s_nop 0
	global_load_lds_dwordx4 v[160:161], off
	v_lshl_add_u64 v[160:161], v[218:219], 0, s[4:5]
	s_mov_b32 m0, s26
	s_nop 0
	global_load_lds_dwordx4 v[160:161], off
	s_waitcnt vmcnt(8)
	s_waitcnt lgkmcnt(0)
	s_barrier
	s_setprio 1
	v_mfma_f32_16x16x32_bf16 v[62:65], v[144:147], v[180:183], v[62:65]
	v_mfma_f32_16x16x32_bf16 v[58:61], v[152:155], v[180:183], v[58:61]
	v_mfma_f32_16x16x32_bf16 v[46:49], v[144:147], v[188:191], v[46:49]
	v_mfma_f32_16x16x32_bf16 v[42:45], v[152:155], v[188:191], v[42:45]
	v_mfma_f32_16x16x32_bf16 v[30:33], v[144:147], v[200:203], v[30:33]
	v_mfma_f32_16x16x32_bf16 v[26:29], v[152:155], v[200:203], v[26:29]
	v_mfma_f32_16x16x32_bf16 v[14:17], v[144:147], v[208:211], v[14:17]
	v_mfma_f32_16x16x32_bf16 v[10:13], v[152:155], v[208:211], v[10:13]
	v_mfma_f32_16x16x32_bf16 v[62:65], v[148:151], v[184:187], v[62:65]
	v_mfma_f32_16x16x32_bf16 v[58:61], v[156:159], v[184:187], v[58:61]
	v_mfma_f32_16x16x32_bf16 v[46:49], v[148:151], v[196:199], v[46:49]
	v_mfma_f32_16x16x32_bf16 v[42:45], v[156:159], v[196:199], v[42:45]
	v_mfma_f32_16x16x32_bf16 v[30:33], v[148:151], v[204:207], v[30:33]
	v_mfma_f32_16x16x32_bf16 v[26:29], v[156:159], v[204:207], v[26:29]
	v_mfma_f32_16x16x32_bf16 v[14:17], v[148:151], v[212:215], v[14:17]
	v_mfma_f32_16x16x32_bf16 v[10:13], v[156:159], v[212:215], v[10:13]
	v_mfma_f32_16x16x32_bf16 v[54:57], v[164:167], v[180:183], v[54:57]
	v_mfma_f32_16x16x32_bf16 v[50:53], v[172:175], v[180:183], v[50:53]
	v_mfma_f32_16x16x32_bf16 v[38:41], v[164:167], v[188:191], v[38:41]
	v_mfma_f32_16x16x32_bf16 v[34:37], v[172:175], v[188:191], v[34:37]
	v_mfma_f32_16x16x32_bf16 v[22:25], v[164:167], v[200:203], v[22:25]
	v_mfma_f32_16x16x32_bf16 v[18:21], v[172:175], v[200:203], v[18:21]
	v_mfma_f32_16x16x32_bf16 v[6:9], v[164:167], v[208:211], v[6:9]
	v_mfma_f32_16x16x32_bf16 v[2:5], v[172:175], v[208:211], v[2:5]
	v_mfma_f32_16x16x32_bf16 v[54:57], v[168:171], v[184:187], v[54:57]
	v_mfma_f32_16x16x32_bf16 v[50:53], v[176:179], v[184:187], v[50:53]
	v_mfma_f32_16x16x32_bf16 v[38:41], v[168:171], v[196:199], v[38:41]
	v_mfma_f32_16x16x32_bf16 v[34:37], v[176:179], v[196:199], v[34:37]
	v_mfma_f32_16x16x32_bf16 v[22:25], v[168:171], v[204:207], v[22:25]
	v_mfma_f32_16x16x32_bf16 v[18:21], v[176:179], v[204:207], v[18:21]
	v_mfma_f32_16x16x32_bf16 v[6:9], v[168:171], v[212:215], v[6:9]
	v_mfma_f32_16x16x32_bf16 v[2:5], v[176:179], v[212:215], v[2:5]
	s_setprio 0
	s_barrier
	s_add_i32 s29, s29, 2
	s_add_u32 s10, s10, 0x100
	s_addc_u32 s11, s11, 0
	s_cmpk_lt_u32 s29, 0x7e
	s_cbranch_scc1 .LBB0_1031
	s_waitcnt vmcnt(0)
	s_cmpk_gt_u32 s19, 0xff
	s_cbranch_scc1 .LBB0_1034
	s_barrier
